# sub-barriers skip the L2 writeback when a run-time XCC census shows the group shares one XCD
# speedup vs baseline: 1.0174x; 1.0174x over previous
.LBB0_2:
	s_load_dwordx2 s[2:3], s[0:1], 0xb8
	v_and_b32_e32 v178, 0x3ff, v0
	v_cmp_gt_u32_e32 vcc, 32, v178
	s_waitcnt lgkmcnt(0)
	v_writelane_b32 v249, s2, 4
	s_nop 1
	v_writelane_b32 v249, s3, 5
	s_load_dword s2, s[0:1], 0xc8
	s_waitcnt lgkmcnt(0)
	v_writelane_b32 v249, s2, 6
	s_and_saveexec_b64 s[2:3], vcc
	v_lshl_add_u32 v1, v178, 2, 0
	v_add_u32_e32 v1, 0x20140, v1
	v_mov_b32_e32 v2, 0
	ds_write_b32 v1, v2
	s_or_b64 exec, exec, s[2:3]
	s_add_u32 s2, s82, 0x4000
	s_addc_u32 s3, s83, 0
	v_writelane_b32 v249, s2, 7
	s_waitcnt lgkmcnt(0)
	s_barrier
	v_writelane_b32 v249, s3, 8
	s_getreg_b32 s2, hwreg(HW_REG_XCC_ID, 0, 4)
	s_and_b32 s2, s2, 15
	v_writelane_b32 v249, s2, 9
	v_cmp_eq_u32_e64 s[12:13], 0, v178
	s_mov_b64 s[2:3], exec
	s_nop 0
	v_writelane_b32 v249, s12, 10
	s_nop 1
	v_writelane_b32 v249, s13, 11
	s_and_b64 s[12:13], s[2:3], s[12:13]
	s_mov_b64 exec, s[12:13]
	s_cbranch_execz .LBB0_7
	s_mov_b64 s[12:13], exec
	v_mbcnt_lo_u32_b32 v1, s12, 0
	v_mbcnt_hi_u32_b32 v1, s13, v1
	v_cmp_eq_u32_e32 vcc, 0, v1
	s_and_b64 s[14:15], exec, vcc
	s_mov_b64 exec, s[14:15]
	s_cbranch_execz .LBB0_7
	v_readlane_b32 s14, v249, 9
	s_bcnt1_i32_b64 s12, s[12:13]
	s_lshl_b32 s14, s14, 8
	v_mov_b32_e32 v2, s12
	v_readlane_b32 s12, v249, 7
	v_mov_b32_e32 v1, s14
	v_readlane_b32 s13, v249, 8
	s_nop 4
	global_atomic_add v1, v2, s[12:13] offset:1024
	v_readlane_b32 s98, v249, 9
	s_lshl_b32 s98, 1, s98
	v_mov_b32_e32 v3, s98
	s_and_b32 s99, s81, 63
	s_lshl_b32 s99, s99, 2
	s_add_u32 s99, s99, 0x30000
	v_mov_b32_e32 v4, s99
	global_atomic_or v4, v3, s[82:83]
	s_and_b32 s99, s81, 7
	s_lshl_b32 s99, s99, 2
	s_add_u32 s99, s99, 0x30400
	v_mov_b32_e32 v4, s99
	global_atomic_or v4, v3, s[82:83]

.LBB0_199:
	v_readlane_b32 s2, v249, 4
	v_readlane_b32 s3, v249, 5
	s_cmp_lt_i32 s2, 2
	s_cselect_b64 s[0:1], -1, 0
	s_cmp_gt_i32 s3, 1
	s_cselect_b64 s[2:3], -1, 0
	s_and_b64 s[0:1], s[0:1], s[2:3]
	s_andn2_b64 vcc, exec, s[0:1]
	s_cbranch_vccnz .LBB0_428
	s_and_b32 s98, s81, 63
	s_lshl_b32 s98, s98, 2
	s_add_u32 s98, s98, 0x30000
	s_and_b32 s99, s81, 7
	s_lshl_b32 s99, s99, 2
	s_add_u32 s99, s99, 0x30400
	v_mov_b32_e32 v250, s98
	v_mov_b32_e32 v251, s99
	global_load_dword v250, v250, s[82:83] sc1
	global_load_dword v251, v251, s[82:83] sc1
	s_waitcnt vmcnt(0)
	v_readfirstlane_b32 s98, v250
	v_readfirstlane_b32 s99, v251
	s_bcnt1_i32_b32 s98, s98
	s_bcnt1_i32_b32 s99, s99
	s_cmp_eq_u32 s98, 1
	s_cselect_b32 s98, 1, 0
	s_cmp_eq_u32 s99, 1
	s_cselect_b32 s99, 1, 0
	v_writelane_b32 v250, s98, 0
	v_writelane_b32 v250, s99, 1
	s_mov_b64 s[2:3], s[82:83]
	v_mov_b32_e32 v1, v178
	s_cmpk_lt_i32 s81, 0x200
	s_cselect_b64 s[4:5], -1, 0
	s_cmpk_gt_i32 s81, 0x1ff
	v_readfirstlane_b32 s6, v1
	s_cbranch_scc1 .LBB0_206
	s_ashr_i32 s0, s81, 31
	s_lshr_b32 s0, s0, 29
	s_add_i32 s7, s81, s0
	s_and_b32 s0, s7, -8
	s_sub_i32 s8, s81, s0
	s_cmp_gt_i32 s8, -1
	s_cbranch_scc0 .LBB0_203
	s_lshl_b32 s9, s8, 6
	s_cbranch_execz .LBB0_204
	s_branch .LBB0_205

.LBB0_396:
	s_and_b64 vcc, exec, s[0:1]
	s_cbranch_vccz .LBB0_414
	s_waitcnt vmcnt(0)
	s_waitcnt vmcnt(0) lgkmcnt(0)
	s_barrier
	s_mov_b64 s[0:1], exec
	v_readlane_b32 s2, v249, 10
	v_readlane_b32 s3, v249, 11
	s_and_b64 s[2:3], s[0:1], s[2:3]
	s_mov_b64 exec, s[2:3]
	s_cbranch_execz .LBB0_413
	s_lshl_b32 s2, s81, 8
	s_and_b32 s2, s2, 0x3f00
	s_mov_b64 s[4:5], exec
	s_add_u32 s2, s82, s2
	s_addc_u32 s3, s83, 0
	v_readlane_b32 s98, v250, 0
	s_cmp_lg_u32 s98, 0
	s_cbranch_scc1 .Lskip_wbl2_0
	buffer_wbl2 sc1
.Lskip_wbl2_0:
	s_waitcnt vmcnt(0)
	v_mbcnt_lo_u32_b32 v1, s4, 0
	s_add_u32 s2, s2, 0x10000
	v_mbcnt_hi_u32_b32 v2, s5, v1
	s_addc_u32 s3, s3, 0
	v_cmp_eq_u32_e32 vcc, 0, v2
	s_and_saveexec_b64 s[6:7], vcc
	s_cbranch_execz .LBB0_400
	s_bcnt1_i32_b64 s4, s[4:5]
	v_mov_b32_e32 v1, 0
	v_mov_b32_e32 v3, s4
	global_atomic_add v3, v1, v3, s[2:3] sc0

.LBB0_629:
	s_and_b64 vcc, exec, s[0:1]
	s_cbranch_vccz .LBB0_647
	s_waitcnt vmcnt(0)
	s_waitcnt vmcnt(0)
	s_barrier
	s_mov_b64 s[0:1], exec
	v_readlane_b32 s2, v249, 10
	v_readlane_b32 s3, v249, 11
	s_and_b64 s[2:3], s[0:1], s[2:3]
	s_mov_b64 exec, s[2:3]
	s_cbranch_execz .LBB0_646
	s_lshl_b32 s2, s81, 8
	s_and_b32 s2, s2, 0x3f00
	s_mov_b64 s[4:5], exec
	s_add_u32 s2, s82, s2
	s_addc_u32 s3, s83, 0
	v_readlane_b32 s98, v250, 0
	s_cmp_lg_u32 s98, 0
	s_cbranch_scc1 .Lskip_wbl2_1
	buffer_wbl2 sc1

.LBB0_1611:
	s_and_b64 vcc, exec, s[0:1]
	s_cbranch_vccz .LBB0_1629
	s_waitcnt vmcnt(0)
	s_waitcnt vmcnt(0)
	s_barrier
	s_mov_b64 s[0:1], exec
	v_readlane_b32 s2, v249, 10
	v_readlane_b32 s3, v249, 11
	s_and_b64 s[2:3], s[0:1], s[2:3]
	s_mov_b64 exec, s[2:3]
	s_cbranch_execz .LBB0_1628
	s_lshl_b32 s2, s81, 8
	s_and_b32 s2, s2, 0x700
	s_mov_b64 s[4:5], exec
	s_add_u32 s2, s82, s2
	s_addc_u32 s3, s83, 0
	v_readlane_b32 s98, v250, 1
	s_cmp_lg_u32 s98, 0
	s_cbranch_scc1 .Lskip_wbl2_3
	buffer_wbl2 sc1
.Lskip_wbl2_3:
	s_waitcnt vmcnt(0)
	v_mbcnt_lo_u32_b32 v1, s4, 0
	s_add_u32 s2, s2, 0x20000
	v_mbcnt_hi_u32_b32 v2, s5, v1
	s_addc_u32 s3, s3, 0
	v_cmp_eq_u32_e32 vcc, 0, v2
	s_and_saveexec_b64 s[6:7], vcc
	s_cbranch_execz .LBB0_1615
	s_bcnt1_i32_b64 s4, s[4:5]
	v_mov_b32_e32 v1, 0
	v_mov_b32_e32 v3, s4
	global_atomic_add v3, v1, v3, s[2:3] sc0

	.amdhsa_kernel _Z8yoco_fwd4Args
		.amdhsa_group_segment_fixed_size 0
		.amdhsa_private_segment_fixed_size 0
		.amdhsa_kernarg_size 448
		.amdhsa_user_sgpr_count 2
		.amdhsa_user_sgpr_dispatch_ptr 0
		.amdhsa_user_sgpr_queue_ptr 0
		.amdhsa_user_sgpr_kernarg_segment_ptr 1
		.amdhsa_user_sgpr_dispatch_id 0
		.amdhsa_user_sgpr_kernarg_preload_length 0
		.amdhsa_user_sgpr_kernarg_preload_offset 0
		.amdhsa_user_sgpr_private_segment_size 0
		.amdhsa_uses_dynamic_stack 0
		.amdhsa_enable_private_segment 0
		.amdhsa_system_sgpr_workgroup_id_x 1
		.amdhsa_system_sgpr_workgroup_id_y 0
		.amdhsa_system_sgpr_workgroup_id_z 0
		.amdhsa_system_sgpr_workgroup_info 0
		.amdhsa_system_vgpr_workitem_id 2
		.amdhsa_next_free_vgpr 252
		.amdhsa_next_free_sgpr 102
		.amdhsa_accum_offset 252
		.amdhsa_reserve_vcc 1
		.amdhsa_float_round_mode_32 0
		.amdhsa_float_round_mode_16_64 0
		.amdhsa_float_denorm_mode_32 3
		.amdhsa_float_denorm_mode_16_64 3
		.amdhsa_dx10_clamp 1
		.amdhsa_ieee_mode 1
		.amdhsa_fp16_overflow 0
		.amdhsa_tg_split 0
		.amdhsa_exception_fp_ieee_invalid_op 0
		.amdhsa_exception_fp_denorm_src 0
		.amdhsa_exception_fp_ieee_div_zero 0
		.amdhsa_exception_fp_ieee_overflow 0
		.amdhsa_exception_fp_ieee_underflow 0
		.amdhsa_exception_fp_ieee_inexact 0
		.amdhsa_exception_int_div_zero 0
	.end_amdhsa_kernel

.Lfunc_end0:
	.size	_Z8yoco_fwd4Args, .Lfunc_end0-_Z8yoco_fwd4Args
	.set _Z8yoco_fwd4Args.num_vgpr, 252
	.set _Z8yoco_fwd4Args.num_agpr, 0
	.set _Z8yoco_fwd4Args.numbered_sgpr, 102
	.set _Z8yoco_fwd4Args.num_named_barrier, 0
	.set _Z8yoco_fwd4Args.private_seg_size, 0
	.set _Z8yoco_fwd4Args.uses_vcc, 1
	.set _Z8yoco_fwd4Args.uses_flat_scratch, 0
	.set _Z8yoco_fwd4Args.has_dyn_sized_stack, 0
	.set _Z8yoco_fwd4Args.has_recursion, 0
	.set _Z8yoco_fwd4Args.has_indirect_call, 0

amdhsa.kernels:
  - .agpr_count:     0
    .args:
      - .offset:         0
        .size:           192
        .value_kind:     by_value
      - .offset:         192
        .size:           4
        .value_kind:     hidden_block_count_x
      - .offset:         196
        .size:           4
        .value_kind:     hidden_block_count_y
      - .offset:         200
        .size:           4
        .value_kind:     hidden_block_count_z
      - .offset:         204
        .size:           2
        .value_kind:     hidden_group_size_x
      - .offset:         206
        .size:           2
        .value_kind:     hidden_group_size_y
      - .offset:         208
        .size:           2
        .value_kind:     hidden_group_size_z
      - .offset:         210
        .size:           2
        .value_kind:     hidden_remainder_x
      - .offset:         212
        .size:           2
        .value_kind:     hidden_remainder_y
      - .offset:         214
        .size:           2
        .value_kind:     hidden_remainder_z
      - .offset:         232
        .size:           8
        .value_kind:     hidden_global_offset_x
      - .offset:         240
        .size:           8
        .value_kind:     hidden_global_offset_y
      - .offset:         248
        .size:           8
        .value_kind:     hidden_global_offset_z
      - .offset:         256
        .size:           2
        .value_kind:     hidden_grid_dims
      - .offset:         280
        .size:           8
        .value_kind:     hidden_multigrid_sync_arg
      - .offset:         312
        .size:           4
        .value_kind:     hidden_dynamic_lds_size
    .group_segment_fixed_size: 0
    .kernarg_segment_align: 8
    .kernarg_segment_size: 448
    .language:       OpenCL C
    .language_version:
      - 2
      - 0
    .max_flat_workgroup_size: 512
    .name:           _Z8yoco_fwd4Args
    .private_segment_fixed_size: 0
    .sgpr_count:     108
    .sgpr_spill_count: 83
    .symbol:         _Z8yoco_fwd4Args.kd
    .uniform_work_group_size: 1
    .uses_dynamic_stack: false
    .vgpr_count:     252
    .vgpr_spill_count: 0
    .wavefront_size: 64
